# attention tile loop: LDS reads prefetched 6 deep for QK and PV (counted lgkmcnt), softmax code unchanged
# speedup vs baseline: 1.0199x; 1.0199x over previous
.LBB0_1003:
	s_or_b64 exec, exec, s[10:11]
	s_bitcmp1_b32 s29, 0
	s_cselect_b32 s8, 0xa800, 0
	v_add_u32_e32 v116, s8, v198
	ds_read_b128 v[116:119], v116
	v_add_u32_e32 v124, s8, v199
	ds_read_b128 v[124:127], v124
	v_add_u32_e32 v128, s8, v200
	ds_read_b128 v[128:131], v128
	v_add_u32_e32 v136, s8, v201
	ds_read_b128 v[136:139], v136
	v_add_u32_e32 v132, s8, v225
	ds_read_b128 v[132:135], v132
	v_add_u32_e32 v140, s8, v226
	ds_read_b128 v[140:143], v140
	s_waitcnt lgkmcnt(5)
	v_mfma_f32_16x16x32_bf16 v[112:115], v[116:119], v[104:107], 0
	v_mfma_f32_16x16x32_bf16 v[120:123], v[116:119], v[108:111], 0
	v_add_u32_e32 v204, s8, v234
	ds_read_b128 v[204:207], v204
	s_waitcnt lgkmcnt(5)
	v_mfma_f32_16x16x32_bf16 v[112:115], v[124:127], v[96:99], v[112:115]
	v_mfma_f32_16x16x32_bf16 v[120:123], v[124:127], v[100:103], v[120:123]
	v_add_u32_e32 v208, s8, v235
	ds_read_b128 v[208:211], v208
	s_waitcnt lgkmcnt(5)
	v_mfma_f32_16x16x32_bf16 v[112:115], v[128:131], v[88:91], v[112:115]
	v_mfma_f32_16x16x32_bf16 v[120:123], v[128:131], v[92:95], v[120:123]
	v_add_u32_e32 v128, s8, v236
	ds_read_b128 v[128:131], v128
	s_waitcnt lgkmcnt(5)
	v_mfma_f32_16x16x32_bf16 v[112:115], v[136:139], v[80:83], v[112:115]
	v_mfma_f32_16x16x32_bf16 v[120:123], v[136:139], v[84:87], v[120:123]
	v_add_u32_e32 v136, s8, v237
	ds_read_b128 v[136:139], v136
	s_waitcnt lgkmcnt(5)
	v_mfma_f32_16x16x32_bf16 v[112:115], v[132:135], v[72:75], v[112:115]
	v_mfma_f32_16x16x32_bf16 v[120:123], v[132:135], v[76:79], v[120:123]
	v_add_u32_e32 v132, s8, v238
	ds_read_b128 v[132:135], v132
	s_waitcnt lgkmcnt(5)
	v_mfma_f32_16x16x32_bf16 v[112:115], v[140:143], v[64:67], v[112:115]
	v_mfma_f32_16x16x32_bf16 v[120:123], v[140:143], v[68:71], v[120:123]
	v_add_u32_e32 v140, s8, v239
	ds_read_b128 v[140:143], v140
	s_waitcnt lgkmcnt(5)
	v_mfma_f32_16x16x32_bf16 v[116:119], v[204:207], v[104:107], 0
	v_mfma_f32_16x16x32_bf16 v[124:127], v[204:207], v[108:111], 0
	v_add_u32_e32 v204, s8, v240
	ds_read_b128 v[204:207], v204
	s_waitcnt lgkmcnt(5)
	v_mfma_f32_16x16x32_bf16 v[116:119], v[208:211], v[96:99], v[116:119]
	v_mfma_f32_16x16x32_bf16 v[124:127], v[208:211], v[100:103], v[124:127]
	v_add_u32_e32 v208, s8, v241
	ds_read_b128 v[208:211], v208
	s_waitcnt lgkmcnt(5)
	v_mfma_f32_16x16x32_bf16 v[116:119], v[128:131], v[88:91], v[116:119]
	v_mfma_f32_16x16x32_bf16 v[124:127], v[128:131], v[92:95], v[124:127]
	s_waitcnt lgkmcnt(4)
	v_mfma_f32_16x16x32_bf16 v[116:119], v[136:139], v[80:83], v[116:119]
	v_mfma_f32_16x16x32_bf16 v[124:127], v[136:139], v[84:87], v[124:127]
	s_waitcnt lgkmcnt(3)
	v_mfma_f32_16x16x32_bf16 v[116:119], v[132:135], v[72:75], v[116:119]
	v_mfma_f32_16x16x32_bf16 v[124:127], v[132:135], v[76:79], v[124:127]
	v_add_u32_e32 v132, s8, v242
	ds_read_b128 v[132:135], v132
	s_waitcnt lgkmcnt(3)
	v_mfma_f32_16x16x32_bf16 v[116:119], v[140:143], v[64:67], v[116:119]
	v_mfma_f32_16x16x32_bf16 v[124:127], v[140:143], v[68:71], v[124:127]
	v_add_u32_e32 v140, s8, v243
	ds_read_b128 v[140:143], v140
	s_waitcnt lgkmcnt(3)
	v_mfma_f32_16x16x32_bf16 v[136:139], v[204:207], v[104:107], 0
	v_mfma_f32_16x16x32_bf16 v[128:131], v[204:207], v[108:111], 0
	v_add_u32_e32 v204, s8, v244
	ds_read_b128 v[204:207], v204
	s_waitcnt lgkmcnt(3)
	v_mfma_f32_16x16x32_bf16 v[136:139], v[208:211], v[96:99], v[136:139]
	v_mfma_f32_16x16x32_bf16 v[128:131], v[208:211], v[100:103], v[128:131]
	v_add_u32_e32 v208, s8, v245
	ds_read_b128 v[208:211], v208
	s_waitcnt lgkmcnt(3)
	v_mfma_f32_16x16x32_bf16 v[136:139], v[132:135], v[88:91], v[136:139]
	v_mfma_f32_16x16x32_bf16 v[128:131], v[132:135], v[92:95], v[128:131]
	s_waitcnt lgkmcnt(2)
	v_mfma_f32_16x16x32_bf16 v[136:139], v[140:143], v[80:83], v[136:139]
	v_mfma_f32_16x16x32_bf16 v[128:131], v[140:143], v[84:87], v[128:131]
	s_waitcnt lgkmcnt(1)
	v_mfma_f32_16x16x32_bf16 v[136:139], v[204:207], v[72:75], v[136:139]
	v_mfma_f32_16x16x32_bf16 v[128:131], v[204:207], v[76:79], v[128:131]
	v_add_u32_e32 v204, s8, v246
	ds_read_b128 v[204:207], v204
	s_waitcnt lgkmcnt(1)
	v_mfma_f32_16x16x32_bf16 v[136:139], v[208:211], v[64:67], v[136:139]
	v_mfma_f32_16x16x32_bf16 v[128:131], v[208:211], v[68:71], v[128:131]
	v_add_u32_e32 v208, s8, v247
	ds_read_b128 v[208:211], v208
	s_waitcnt lgkmcnt(1)
	v_mfma_f32_16x16x32_bf16 v[140:143], v[204:207], v[104:107], 0
	v_mfma_f32_16x16x32_bf16 v[132:135], v[204:207], v[108:111], 0
	v_add_u32_e32 v204, s8, v248
	ds_read_b128 v[204:207], v204
	s_waitcnt lgkmcnt(1)
	v_mfma_f32_16x16x32_bf16 v[140:143], v[208:211], v[96:99], v[140:143]
	v_mfma_f32_16x16x32_bf16 v[132:135], v[208:211], v[100:103], v[132:135]
	v_add_u32_e32 v208, s8, v249
	ds_read_b128 v[208:211], v208
	s_waitcnt lgkmcnt(1)
	v_mfma_f32_16x16x32_bf16 v[140:143], v[204:207], v[88:91], v[140:143]
	v_mfma_f32_16x16x32_bf16 v[132:135], v[204:207], v[92:95], v[132:135]
	v_add_u32_e32 v204, s8, v250
	ds_read_b128 v[204:207], v204
	s_waitcnt lgkmcnt(1)
	v_mfma_f32_16x16x32_bf16 v[140:143], v[208:211], v[80:83], v[140:143]
	v_mfma_f32_16x16x32_bf16 v[132:135], v[208:211], v[84:87], v[132:135]
	v_add_u32_e32 v208, s8, v251
	ds_read_b128 v[208:211], v208
	s_waitcnt lgkmcnt(1)
	v_mfma_f32_16x16x32_bf16 v[140:143], v[204:207], v[72:75], v[140:143]
	v_mfma_f32_16x16x32_bf16 v[132:135], v[204:207], v[76:79], v[132:135]
	s_waitcnt lgkmcnt(0)
	v_mfma_f32_16x16x32_bf16 v[140:143], v[208:211], v[64:67], v[140:143]
	v_mfma_f32_16x16x32_bf16 v[132:135], v[208:211], v[68:71], v[132:135]
	s_nop 7
	v_max_f32_e32 v157, v112, v112
	v_max_f32_e32 v195, v114, v114
	v_max_f32_e32 v155, v113, v113
	v_max_f32_e32 v155, v157, v155
	v_max_f32_e32 v157, v115, v115
	v_max_f32_e32 v157, v195, v157
	v_max_f32_e32 v195, v119, v119
	v_max_f32_e32 v204, v118, v118
	v_max_f32_e32 v195, v204, v195
	v_max3_f32 v195, v116, v117, v195
	v_max3_f32 v155, v155, v157, v195
	v_max_f32_e32 v157, v139, v139
	v_max_f32_e32 v195, v138, v138
	v_max_f32_e32 v157, v195, v157
	v_max_f32_e32 v195, v143, v143
	v_max_f32_e32 v204, v142, v142
	v_max_f32_e32 v195, v204, v195
	v_max3_f32 v157, v136, v137, v157
	v_max3_f32 v195, v140, v141, v195
	v_max3_f32 v155, v155, v157, v195
	v_sub_f32_e32 v157, v155, v162
	v_cmp_ge_f32_e32 vcc, s89, v157
	s_cmp_eq_u64 vcc, exec
	s_cbranch_scc1 .LBB0_1005
	v_and_b32_e32 v195, 64, v227
	v_xor_b32_e32 v157, 16, v227
	v_add_u32_e32 v195, 64, v195
	v_cmp_lt_i32_e32 vcc, v157, v195
	s_nop 1
	v_cndmask_b32_e32 v157, v227, v157, vcc
	v_lshlrev_b32_e32 v157, 2, v157
	ds_bpermute_b32 v157, v157, v155
	v_max_f32_e32 v155, v155, v155
	s_waitcnt lgkmcnt(0)
	v_max_f32_e32 v157, v157, v157
	v_max_f32_e32 v155, v155, v157
	v_xor_b32_e32 v157, 32, v227
	v_cmp_lt_i32_e32 vcc, v157, v195
	s_nop 1
	v_cndmask_b32_e32 v157, v227, v157, vcc
	v_lshlrev_b32_e32 v157, 2, v157
	ds_bpermute_b32 v157, v157, v155
	s_waitcnt lgkmcnt(0)
	v_max3_f32 v155, v162, v155, v157
	v_sub_f32_e32 v157, v162, v155
	v_mul_f32_e32 v157, 0x3dd53b94, v157
	v_exp_f32_e32 v162, v157
	s_nop 0
	v_mul_f32_e32 v156, v156, v162
	v_pk_mul_f32 v[62:63], v[62:63], v[162:163] op_sel_hi:[1,0]
	v_pk_mul_f32 v[60:61], v[60:61], v[162:163] op_sel_hi:[1,0]
	v_pk_mul_f32 v[54:55], v[54:55], v[162:163] op_sel_hi:[1,0]
	v_pk_mul_f32 v[52:53], v[52:53], v[162:163] op_sel_hi:[1,0]
	v_pk_mul_f32 v[46:47], v[46:47], v[162:163] op_sel_hi:[1,0]
	v_pk_mul_f32 v[44:45], v[44:45], v[162:163] op_sel_hi:[1,0]
	v_pk_mul_f32 v[38:39], v[38:39], v[162:163] op_sel_hi:[1,0]
	v_pk_mul_f32 v[36:37], v[36:37], v[162:163] op_sel_hi:[1,0]
	v_pk_mul_f32 v[26:27], v[26:27], v[162:163] op_sel_hi:[1,0]
	v_pk_mul_f32 v[24:25], v[24:25], v[162:163] op_sel_hi:[1,0]
	v_pk_mul_f32 v[18:19], v[18:19], v[162:163] op_sel_hi:[1,0]
	v_pk_mul_f32 v[16:17], v[16:17], v[162:163] op_sel_hi:[1,0]
	v_pk_mul_f32 v[10:11], v[10:11], v[162:163] op_sel_hi:[1,0]
	v_pk_mul_f32 v[8:9], v[8:9], v[162:163] op_sel_hi:[1,0]
	v_pk_mul_f32 v[2:3], v[2:3], v[162:163] op_sel_hi:[1,0]
	v_pk_mul_f32 v[0:1], v[0:1], v[162:163] op_sel_hi:[1,0]
	v_mov_b32_e32 v162, v155

.LBB0_1007:
	v_add_f32_e32 v155, 0, v155
	v_add_f32_e32 v155, v204, v155
	v_add_f32_e32 v155, v205, v155
	v_add_f32_e32 v155, v206, v155
	v_add_f32_e32 v155, v207, v155
	v_add_f32_e32 v155, v208, v155
	v_add_f32_e32 v155, v230, v155
	v_add_f32_e32 v155, v195, v155
	v_add_f32_e32 v136, v136, v155
	v_add_f32_e32 v136, v137, v136
	v_add_f32_e32 v136, v138, v136
	v_mul_f32_e32 v155, 0xbdd53b94, v203
	v_add_f32_e32 v136, v139, v136
	v_fmamk_f32 v120, v120, 0x3dd53b94, v155
	v_add_f32_e32 v136, v140, v136
	v_exp_f32_e32 v120, v120
	v_fmamk_f32 v121, v121, 0x3dd53b94, v155
	v_add_f32_e32 v136, v141, v136
	v_exp_f32_e32 v121, v121
	v_fmamk_f32 v122, v122, 0x3dd53b94, v155
	v_add_f32_e32 v136, v142, v136
	v_exp_f32_e32 v122, v122
	v_fmamk_f32 v123, v123, 0x3dd53b94, v155
	v_add_f32_e32 v136, v143, v136
	v_exp_f32_e32 v123, v123
	v_fmamk_f32 v124, v124, 0x3dd53b94, v155
	v_add_f32_e32 v156, v156, v136
	v_add_f32_e32 v136, 0, v120
	v_exp_f32_e32 v137, v124
	v_add_f32_e32 v136, v121, v136
	v_add_f32_e32 v136, v122, v136
	v_add_f32_e32 v136, v123, v136
	v_fmamk_f32 v125, v125, 0x3dd53b94, v155
	v_add_f32_e32 v124, v137, v136
	v_exp_f32_e32 v136, v125
	v_fmamk_f32 v125, v126, 0x3dd53b94, v155
	v_exp_f32_e32 v138, v125
	v_fmamk_f32 v125, v127, 0x3dd53b94, v155
	v_exp_f32_e32 v127, v125
	v_fmamk_f32 v125, v128, 0x3dd53b94, v155
	v_exp_f32_e32 v128, v125
	v_fmamk_f32 v125, v129, 0x3dd53b94, v155
	v_add_f32_e32 v124, v136, v124
	v_exp_f32_e32 v129, v125
	v_fmamk_f32 v125, v130, 0x3dd53b94, v155
	v_add_f32_e32 v124, v138, v124
	v_exp_f32_e32 v130, v125
	v_fmamk_f32 v125, v131, 0x3dd53b94, v155
	v_add_f32_e32 v124, v127, v124
	v_exp_f32_e32 v131, v125
	v_fmamk_f32 v125, v132, 0x3dd53b94, v155
	v_add_f32_e32 v124, v128, v124
	v_exp_f32_e32 v132, v125
	v_fmamk_f32 v125, v133, 0x3dd53b94, v155
	v_add_f32_e32 v124, v129, v124
	v_exp_f32_e32 v133, v125
	v_fmamk_f32 v125, v134, 0x3dd53b94, v155
	v_add_f32_e32 v124, v130, v124
	v_exp_f32_e32 v134, v125
	v_fmamk_f32 v125, v135, 0x3dd53b94, v155
	v_add_f32_e32 v124, v131, v124
	v_exp_f32_e32 v135, v125
	v_add_f32_e32 v124, v132, v124
	v_add_f32_e32 v124, v133, v124
	v_add_f32_e32 v124, v134, v124
	v_add_f32_e32 v124, v135, v124
	v_add_f32_e32 v154, v154, v124
	v_cvt_pk_bf16_f32 v124, v120, v121
	v_cvt_pk_bf16_f32 v125, v122, v123
	v_cvt_pk_bf16_f32 v126, v137, v136
	v_cvt_pk_bf16_f32 v127, v138, v127
	v_cvt_pk_bf16_f32 v120, v128, v129
	v_cvt_pk_bf16_f32 v121, v130, v131
	v_cvt_pk_bf16_f32 v122, v132, v133
	v_cvt_pk_bf16_f32 v123, v134, v135
	v_add3_u32 v230, s8, v144, v202
	ds_read_b64 v[128:129], v230 offset:24576
	ds_read_b64 v[130:131], v230 offset:24608
	ds_read_b64 v[132:133], v230 offset:24640
	ds_read_b64 v[134:135], v230 offset:24672
	ds_read_b64 v[136:137], v230 offset:26880
	ds_read_b64 v[138:139], v230 offset:26912
	ds_read_b64 v[140:141], v230 offset:26944
	ds_read_b64 v[142:143], v230 offset:26976
	ds_read_b64 v[204:205], v230 offset:29184
	ds_read_b64 v[206:207], v230 offset:29216
	ds_read_b64 v[208:209], v230 offset:29248
	ds_read_b64 v[210:211], v230 offset:29280
	s_waitcnt lgkmcnt(10)
	v_mfma_f32_16x16x32_bf16 v[60:63], v[128:131], v[116:119], v[60:63]
	v_mfma_f32_16x16x32_bf16 v[56:59], v[128:131], v[124:127], v[56:59]
	ds_read_b64 v[128:129], v230 offset:31488
	ds_read_b64 v[130:131], v230 offset:31520
	s_waitcnt lgkmcnt(10)
	v_mfma_f32_16x16x32_bf16 v[60:63], v[132:135], v[112:115], v[60:63]
	v_mfma_f32_16x16x32_bf16 v[56:59], v[132:135], v[120:123], v[56:59]
	ds_read_b64 v[132:133], v230 offset:31552
	ds_read_b64 v[134:135], v230 offset:31584
	s_waitcnt lgkmcnt(10)
	v_mfma_f32_16x16x32_bf16 v[52:55], v[136:139], v[116:119], v[52:55]
	v_mfma_f32_16x16x32_bf16 v[48:51], v[136:139], v[124:127], v[48:51]
	ds_read_b64 v[136:137], v230 offset:33792
	ds_read_b64 v[138:139], v230 offset:33824
	s_waitcnt lgkmcnt(10)
	v_mfma_f32_16x16x32_bf16 v[52:55], v[140:143], v[112:115], v[52:55]
	v_mfma_f32_16x16x32_bf16 v[48:51], v[140:143], v[120:123], v[48:51]
	ds_read_b64 v[140:141], v230 offset:33856
	ds_read_b64 v[142:143], v230 offset:33888
	s_waitcnt lgkmcnt(10)
	v_mfma_f32_16x16x32_bf16 v[44:47], v[204:207], v[116:119], v[44:47]
	v_mfma_f32_16x16x32_bf16 v[40:43], v[204:207], v[124:127], v[40:43]
	ds_read_b64 v[204:205], v230 offset:36096
	ds_read_b64 v[206:207], v230 offset:36128
	s_waitcnt lgkmcnt(10)
	v_mfma_f32_16x16x32_bf16 v[44:47], v[208:211], v[112:115], v[44:47]
	v_mfma_f32_16x16x32_bf16 v[40:43], v[208:211], v[120:123], v[40:43]
	ds_read_b64 v[208:209], v230 offset:36160
	ds_read_b64 v[210:211], v230 offset:36192
	s_waitcnt lgkmcnt(10)
	v_mfma_f32_16x16x32_bf16 v[36:39], v[128:131], v[116:119], v[36:39]
	v_mfma_f32_16x16x32_bf16 v[28:31], v[128:131], v[124:127], v[28:31]
	ds_read_b64 v[128:129], v230 offset:38400
	ds_read_b64 v[130:131], v230 offset:38432
	s_waitcnt lgkmcnt(10)
	v_mfma_f32_16x16x32_bf16 v[36:39], v[132:135], v[112:115], v[36:39]
	v_mfma_f32_16x16x32_bf16 v[28:31], v[132:135], v[120:123], v[28:31]
	ds_read_b64 v[132:133], v230 offset:38464
	ds_read_b64 v[134:135], v230 offset:38496
	s_waitcnt lgkmcnt(10)
	v_mfma_f32_16x16x32_bf16 v[24:27], v[136:139], v[116:119], v[24:27]
	v_mfma_f32_16x16x32_bf16 v[32:35], v[136:139], v[124:127], v[32:35]
	ds_read_b64 v[136:137], v230 offset:40704
	ds_read_b64 v[138:139], v230 offset:40736
	s_waitcnt lgkmcnt(10)
	v_mfma_f32_16x16x32_bf16 v[24:27], v[140:143], v[112:115], v[24:27]
	v_mfma_f32_16x16x32_bf16 v[32:35], v[140:143], v[120:123], v[32:35]
	ds_read_b64 v[140:141], v230 offset:40768
	ds_read_b64 v[142:143], v230 offset:40800
	s_waitcnt lgkmcnt(10)
	v_mfma_f32_16x16x32_bf16 v[16:19], v[204:207], v[116:119], v[16:19]
	v_mfma_f32_16x16x32_bf16 v[20:23], v[204:207], v[124:127], v[20:23]
	s_waitcnt lgkmcnt(8)
	v_mfma_f32_16x16x32_bf16 v[16:19], v[208:211], v[112:115], v[16:19]
	v_mfma_f32_16x16x32_bf16 v[20:23], v[208:211], v[120:123], v[20:23]
	s_waitcnt lgkmcnt(6)
	v_mfma_f32_16x16x32_bf16 v[8:11], v[128:131], v[116:119], v[8:11]
	v_mfma_f32_16x16x32_bf16 v[12:15], v[128:131], v[124:127], v[12:15]
	s_waitcnt lgkmcnt(4)
	v_mfma_f32_16x16x32_bf16 v[8:11], v[132:135], v[112:115], v[8:11]
	v_mfma_f32_16x16x32_bf16 v[12:15], v[132:135], v[120:123], v[12:15]
	s_waitcnt lgkmcnt(2)
	v_mfma_f32_16x16x32_bf16 v[0:3], v[136:139], v[116:119], v[0:3]
	v_mfma_f32_16x16x32_bf16 v[4:7], v[136:139], v[124:127], v[4:7]
	s_waitcnt lgkmcnt(0)
	v_mfma_f32_16x16x32_bf16 v[0:3], v[140:143], v[112:115], v[0:3]
	v_mfma_f32_16x16x32_bf16 v[4:7], v[140:143], v[120:123], v[4:7]
	s_add_i32 s13, s13, 64
	s_add_i32 s27, s27, 64
	s_cmp_eq_u32 s26, s28
	s_waitcnt vmcnt(0) lgkmcnt(0)
	s_barrier
	s_cbranch_scc1 .LBB0_1011
	s_mov_b32 s29, s28
	s_branch .LBB0_999
